# pool_d hand-written: all 30 window loads of an item in flight at once
# speedup vs baseline: 1.0104x; 1.0049x over previous
; __device__ __forceinline__ float bflo(unsigned w) { return __uint_as_float(w << 16); }
; __device__ __forceinline__ float bfhi(unsigned w) { return __uint_as_float(w & 0xffff0000u); }
; template <int W>
; __device__ __forceinline__ void pool_item(const Params& p, const bf16_t* PROJ, bf16_t* D, int r, int c0) {
;     float sum[8], uu[8];
;     const u32x4 v0 = *(const u32x4*)(PROJ + (size_t)r * NQ + c0);
;     uu[0] = bflo(v0.x); uu[1] = bfhi(v0.x); uu[2] = bflo(v0.y); uu[3] = bfhi(v0.y); uu[4] = bflo(v0.z); uu[5] = bfhi(v0.z); uu[6] = bflo(v0.w); uu[7] = bfhi(v0.w);
; #pragma unroll
;     for (int j = 0; j < 8; ++j) sum[j] = uu[j];
;     float cnt;
;     if (r < MP) {
;         const int t = r & 2047; cnt = (float)((t + 1 < W) ? (t + 1) : W);
;         u32x4 v[W - 1];
; #pragma unroll
;         for (int i = 1; i < W; ++i) v[i - 1] = *(const u32x4*)(PROJ + (size_t)(r - (i <= t ? i : 0)) * NQ + c0);
; #pragma unroll
;         for (int i = 1; i < W; ++i) acc8(sum, v[i - 1], (i <= t) ? 1.f : 0.f);
;     ...
;     const float inv = 1.0f / cnt; u32x4 o;
; __device__ __forceinline__ void phase_pool_d(const Params& p, int wave_s) {
;     const bf16_t* PROJ = (const bf16_t*)(p.ws + WS_PROJ); bf16_t* D = (bf16_t*)(p.ws + WS_D);
;     const int total = MR * 32;
;     const int tid = opaque_tid(wave_s);
;     for (int idx = blockIdx.x * 512 + tid; idx < total; idx += gridDim.x * 512) {
;         const int r = idx >> 5, ch = idx & 31;
;         pool_item<2>(p, PROJ, D, r, ch * 8);
;         pool_item<4>(p, PROJ, D, r, 256 + ch * 8);
;         pool_item<8>(p, PROJ, D, r, 512 + ch * 8);
;         pool_item<16>(p, PROJ, D, r, 768 + ch * 8);
;     }
.LBB0_641:
	s_cmp_lt_i32 s18, 3
	s_cselect_b64 s[4:5], -1, 0
	s_and_b64 s[26:27], s[4:5], s[0:1]
	s_andn2_b64 vcc, exec, s[26:27]
	s_cbranch_vccnz .LBB0_787
	s_mov_b64 exec, -1
	s_add_u32 s28, s22, 0xa6aa000
	s_addc_u32 s29, s23, 0
	s_add_u32 s84, s22, 0x64aa000
	s_addc_u32 s85, s23, 0
	v_mbcnt_lo_u32_b32 v0, -1, 0
	v_mbcnt_hi_u32_b32 v0, -1, v0
	v_or_b32_e32 v1, s24, v0
	v_lshl_add_u32 v2, s2, 9, v1
	s_mov_b32 s86, 0
.Lpoold_loop:
	v_lshrrev_b32_e32 v3, 5, v2
	v_and_b32_e32 v4, 0x7ff, v3
	v_and_b32_e32 v5, 31, v2
	v_lshlrev_b32_e32 v5, 4, v5
	v_mul_u32_u24_e32 v6, 0x4800, v3
	v_add_u32_e32 v6, v6, v5
	v_lshl_add_u32 v7, v3, 11, v5
	v_mov_b32_e32 v16, v6
	v_cmp_le_u32_e32 vcc, 1, v4
	v_mov_b32_e32 v8, 0x4800
	s_nop 0
	v_cndmask_b32_e32 v8, 0, v8, vcc
	v_sub_u32_e32 v17, v6, v8
	v_cndmask_b32_e64 v33, 0, 1.0, vcc
	v_cmp_le_u32_e32 vcc, 2, v4
	v_mov_b32_e32 v8, 0x9000
	s_nop 0
	v_cndmask_b32_e32 v8, 0, v8, vcc
	v_sub_u32_e32 v18, v6, v8
	v_cndmask_b32_e64 v34, 0, 1.0, vcc
	v_cmp_le_u32_e32 vcc, 3, v4
	v_mov_b32_e32 v8, 0xd800
	s_nop 0
	v_cndmask_b32_e32 v8, 0, v8, vcc
	v_sub_u32_e32 v19, v6, v8
	v_cndmask_b32_e64 v35, 0, 1.0, vcc
	v_cmp_le_u32_e32 vcc, 4, v4
	v_mov_b32_e32 v8, 0x12000
	s_nop 0
	v_cndmask_b32_e32 v8, 0, v8, vcc
	v_sub_u32_e32 v20, v6, v8
	v_cndmask_b32_e64 v36, 0, 1.0, vcc
	v_cmp_le_u32_e32 vcc, 5, v4
	v_mov_b32_e32 v8, 0x16800
	s_nop 0
	v_cndmask_b32_e32 v8, 0, v8, vcc
	v_sub_u32_e32 v21, v6, v8
	v_cndmask_b32_e64 v37, 0, 1.0, vcc
	v_cmp_le_u32_e32 vcc, 6, v4
	v_mov_b32_e32 v8, 0x1b000
	s_nop 0
	v_cndmask_b32_e32 v8, 0, v8, vcc
	v_sub_u32_e32 v22, v6, v8
	v_cndmask_b32_e64 v38, 0, 1.0, vcc
	v_cmp_le_u32_e32 vcc, 7, v4
	v_mov_b32_e32 v8, 0x1f800
	s_nop 0
	v_cndmask_b32_e32 v8, 0, v8, vcc
	v_sub_u32_e32 v23, v6, v8
	v_cndmask_b32_e64 v39, 0, 1.0, vcc
	v_cmp_le_u32_e32 vcc, 8, v4
	v_mov_b32_e32 v8, 0x24000
	s_nop 0
	v_cndmask_b32_e32 v8, 0, v8, vcc
	v_sub_u32_e32 v24, v6, v8
	v_cndmask_b32_e64 v40, 0, 1.0, vcc
	v_cmp_le_u32_e32 vcc, 9, v4
	v_mov_b32_e32 v8, 0x28800
	s_nop 0
	v_cndmask_b32_e32 v8, 0, v8, vcc
	v_sub_u32_e32 v25, v6, v8
	v_cndmask_b32_e64 v41, 0, 1.0, vcc
	v_cmp_le_u32_e32 vcc, 10, v4
	v_mov_b32_e32 v8, 0x2d000
	s_nop 0
	v_cndmask_b32_e32 v8, 0, v8, vcc
	v_sub_u32_e32 v26, v6, v8
	v_cndmask_b32_e64 v42, 0, 1.0, vcc
	v_cmp_le_u32_e32 vcc, 11, v4
	v_mov_b32_e32 v8, 0x31800
	s_nop 0
	v_cndmask_b32_e32 v8, 0, v8, vcc
	v_sub_u32_e32 v27, v6, v8
	v_cndmask_b32_e64 v43, 0, 1.0, vcc
	v_cmp_le_u32_e32 vcc, 12, v4
	v_mov_b32_e32 v8, 0x36000
	s_nop 0
	v_cndmask_b32_e32 v8, 0, v8, vcc
	v_sub_u32_e32 v28, v6, v8
	v_cndmask_b32_e64 v44, 0, 1.0, vcc
	v_cmp_le_u32_e32 vcc, 13, v4
	v_mov_b32_e32 v8, 0x3a800
	s_nop 0
	v_cndmask_b32_e32 v8, 0, v8, vcc
	v_sub_u32_e32 v29, v6, v8
	v_cndmask_b32_e64 v45, 0, 1.0, vcc
	v_cmp_le_u32_e32 vcc, 14, v4
	v_mov_b32_e32 v8, 0x3f000
	s_nop 0
	v_cndmask_b32_e32 v8, 0, v8, vcc
	v_sub_u32_e32 v30, v6, v8
	v_cndmask_b32_e64 v46, 0, 1.0, vcc
	v_cmp_le_u32_e32 vcc, 15, v4
	v_mov_b32_e32 v8, 0x43800
	s_nop 0
	v_cndmask_b32_e32 v8, 0, v8, vcc
	v_sub_u32_e32 v31, v6, v8
	v_cndmask_b32_e64 v47, 0, 1.0, vcc
	global_load_dwordx4 v[64:67], v16, s[28:29]
	global_load_dwordx4 v[68:71], v17, s[28:29]
	global_load_dwordx4 v[72:75], v16, s[28:29] offset:512
	global_load_dwordx4 v[76:79], v17, s[28:29] offset:512
	global_load_dwordx4 v[80:83], v18, s[28:29] offset:512
	global_load_dwordx4 v[84:87], v19, s[28:29] offset:512
	global_load_dwordx4 v[88:91], v16, s[28:29] offset:1024
	global_load_dwordx4 v[92:95], v17, s[28:29] offset:1024
	global_load_dwordx4 v[96:99], v18, s[28:29] offset:1024
	global_load_dwordx4 v[100:103], v19, s[28:29] offset:1024
	global_load_dwordx4 v[104:107], v20, s[28:29] offset:1024
	global_load_dwordx4 v[108:111], v21, s[28:29] offset:1024
	global_load_dwordx4 v[112:115], v22, s[28:29] offset:1024
	global_load_dwordx4 v[116:119], v23, s[28:29] offset:1024
	global_load_dwordx4 v[120:123], v16, s[28:29] offset:1536
	global_load_dwordx4 v[124:127], v17, s[28:29] offset:1536
	global_load_dwordx4 v[128:131], v18, s[28:29] offset:1536
	global_load_dwordx4 v[132:135], v19, s[28:29] offset:1536
	global_load_dwordx4 v[136:139], v20, s[28:29] offset:1536
	global_load_dwordx4 v[140:143], v21, s[28:29] offset:1536
	global_load_dwordx4 v[144:147], v22, s[28:29] offset:1536
	global_load_dwordx4 v[148:151], v23, s[28:29] offset:1536
	global_load_dwordx4 v[152:155], v24, s[28:29] offset:1536
	global_load_dwordx4 v[156:159], v25, s[28:29] offset:1536
	global_load_dwordx4 v[160:163], v26, s[28:29] offset:1536
	global_load_dwordx4 v[164:167], v27, s[28:29] offset:1536
	global_load_dwordx4 v[168:171], v28, s[28:29] offset:1536
	global_load_dwordx4 v[172:175], v29, s[28:29] offset:1536
	global_load_dwordx4 v[176:179], v30, s[28:29] offset:1536
	global_load_dwordx4 v[180:183], v31, s[28:29] offset:1536
	v_add_u32_e32 v9, 1, v4
	v_min_u32_e32 v10, 2, v9
	v_cvt_f32_u32_e32 v11, v10
	v_div_scale_f32 v200, s[88:89], v11, v11, 1.0
	v_rcp_f32_e32 v201, v200
	v_div_scale_f32 v202, vcc, 1.0, v11, 1.0
	v_fma_f32 v203, -v200, v201, 1.0
	v_fmac_f32_e32 v201, v203, v201
	v_mul_f32_e32 v203, v202, v201
	v_fma_f32 v204, -v200, v203, v202
	v_fmac_f32_e32 v203, v204, v201
	v_fma_f32 v200, -v200, v203, v202
	v_div_fmas_f32 v200, v200, v201, v203
	v_div_fixup_f32 v48, v200, v11, 1.0
	v_min_u32_e32 v10, 4, v9
	v_cvt_f32_u32_e32 v11, v10
	v_div_scale_f32 v200, s[88:89], v11, v11, 1.0
	v_rcp_f32_e32 v201, v200
	v_div_scale_f32 v202, vcc, 1.0, v11, 1.0
	v_fma_f32 v203, -v200, v201, 1.0
	v_fmac_f32_e32 v201, v203, v201
	v_mul_f32_e32 v203, v202, v201
	v_fma_f32 v204, -v200, v203, v202
	v_fmac_f32_e32 v203, v204, v201
	v_fma_f32 v200, -v200, v203, v202
	v_div_fmas_f32 v200, v200, v201, v203
	v_div_fixup_f32 v49, v200, v11, 1.0
	v_min_u32_e32 v10, 8, v9
	v_cvt_f32_u32_e32 v11, v10
	v_div_scale_f32 v200, s[88:89], v11, v11, 1.0
	v_rcp_f32_e32 v201, v200
	v_div_scale_f32 v202, vcc, 1.0, v11, 1.0
	v_fma_f32 v203, -v200, v201, 1.0
	v_fmac_f32_e32 v201, v203, v201
	v_mul_f32_e32 v203, v202, v201
	v_fma_f32 v204, -v200, v203, v202
	v_fmac_f32_e32 v203, v204, v201
	v_fma_f32 v200, -v200, v203, v202
	v_div_fmas_f32 v200, v200, v201, v203
	v_div_fixup_f32 v50, v200, v11, 1.0
	v_min_u32_e32 v10, 16, v9
	v_cvt_f32_u32_e32 v11, v10
	v_div_scale_f32 v200, s[88:89], v11, v11, 1.0
	v_rcp_f32_e32 v201, v200
	v_div_scale_f32 v202, vcc, 1.0, v11, 1.0
	v_fma_f32 v203, -v200, v201, 1.0
	v_fmac_f32_e32 v201, v203, v201
	v_mul_f32_e32 v203, v202, v201
	v_fma_f32 v204, -v200, v203, v202
	v_fmac_f32_e32 v203, v204, v201
	v_fma_f32 v200, -v200, v203, v202
	v_div_fmas_f32 v200, v200, v201, v203
	v_div_fixup_f32 v51, v200, v11, 1.0
	s_waitcnt vmcnt(28)
; __device__ __forceinline__ unsigned pk2(float lo, float hi) { const f32x2_t v = {lo, hi}; const bf16x2_t b = __builtin_convertvector(v, bf16x2_t); return __builtin_bit_cast(unsigned, b); }
; __device__ __forceinline__ float bflo(unsigned w) { return __uint_as_float(w << 16); }
; __device__ __forceinline__ float bfhi(unsigned w) { return __uint_as_float(w & 0xffff0000u); }
; template <int W>
; __device__ __forceinline__ void pool_item(const Params& p, const bf16_t* PROJ, bf16_t* D, int r, int c0) {
;     float sum[8], uu[8];
;     const u32x4 v0 = *(const u32x4*)(PROJ + (size_t)r * NQ + c0);
;     uu[0] = bflo(v0.x); uu[1] = bfhi(v0.x); uu[2] = bflo(v0.y); uu[3] = bfhi(v0.y); uu[4] = bflo(v0.z); uu[5] = bfhi(v0.z); uu[6] = bflo(v0.w); uu[7] = bfhi(v0.w);
; #pragma unroll
;     for (int j = 0; j < 8; ++j) sum[j] = uu[j];
;     float cnt;
;     if (r < MP) {
;         const int t = r & 2047; cnt = (float)((t + 1 < W) ? (t + 1) : W);
;         u32x4 v[W - 1];
; #pragma unroll
;         for (int i = 1; i < W; ++i) v[i - 1] = *(const u32x4*)(PROJ + (size_t)(r - (i <= t ? i : 0)) * NQ + c0);
; #pragma unroll
;         for (int i = 1; i < W; ++i) acc8(sum, v[i - 1], (i <= t) ? 1.f : 0.f);
;     } else {
;         const int s = r - MP; cnt = (float)W; const float* sp = p.in[4] + (size_t)s * 15 * 1024 + c0;
;         f32x4 a[W - 1], b[W - 1];
; #pragma unroll
;         for (int i = 0; i < W - 1; ++i) { a[i] = *(const f32x4*)(sp + (size_t)(14 - i) * 1024); b[i] = *(const f32x4*)(sp + (size_t)(14 - i) * 1024 + 4); }
; #pragma unroll
;         for (int i = 0; i < W - 1; ++i) { sum[0] += a[i].x; sum[1] += a[i].y; sum[2] += a[i].z; sum[3] += a[i].w; sum[4] += b[i].x; sum[5] += b[i].y; sum[6] += b[i].z; sum[7] += b[i].w; }
;     }
;     const float inv = 1.0f / cnt; u32x4 o;
;     o.x = pk2(sum[0] * inv - uu[0], sum[1] * inv - uu[1]); o.y = pk2(sum[2] * inv - uu[2], sum[3] * inv - uu[3]);
;     o.z = pk2(sum[4] * inv - uu[4], sum[5] * inv - uu[5]); o.w = pk2(sum[6] * inv - uu[6], sum[7] * inv - uu[7]);
;     *(u32x4*)(D + (size_t)r * 1024 + c0) = o;
	v_lshlrev_b32_e32 v220, 16, v64
	v_and_b32_e32 v221, 0xffff0000, v64
	v_lshlrev_b32_e32 v222, 16, v65
	v_and_b32_e32 v223, 0xffff0000, v65
	v_lshlrev_b32_e32 v224, 16, v66
	v_and_b32_e32 v225, 0xffff0000, v66
	v_lshlrev_b32_e32 v226, 16, v67
	v_and_b32_e32 v227, 0xffff0000, v67
	v_mov_b32_e32 v228, v220
	v_mov_b32_e32 v229, v221
	v_mov_b32_e32 v230, v222
	v_mov_b32_e32 v231, v223
	v_mov_b32_e32 v232, v224
	v_mov_b32_e32 v233, v225
	v_mov_b32_e32 v234, v226
	v_mov_b32_e32 v235, v227
	v_lshlrev_b32_e32 v236, 16, v68
	v_and_b32_e32 v237, 0xffff0000, v68
	v_lshlrev_b32_e32 v238, 16, v69
	v_and_b32_e32 v239, 0xffff0000, v69
	v_lshlrev_b32_e32 v240, 16, v70
	v_and_b32_e32 v241, 0xffff0000, v70
	v_lshlrev_b32_e32 v242, 16, v71
	v_and_b32_e32 v243, 0xffff0000, v71
	v_fmac_f32_e32 v228, v236, v33
	v_fmac_f32_e32 v229, v237, v33
	v_fmac_f32_e32 v230, v238, v33
	v_fmac_f32_e32 v231, v239, v33
	v_fmac_f32_e32 v232, v240, v33
	v_fmac_f32_e32 v233, v241, v33
	v_fmac_f32_e32 v234, v242, v33
	v_fmac_f32_e32 v235, v243, v33
	v_fma_f32 v228, v228, v48, -v220
	v_fma_f32 v229, v229, v48, -v221
	v_fma_f32 v230, v230, v48, -v222
	v_fma_f32 v231, v231, v48, -v223
	v_fma_f32 v232, v232, v48, -v224
	v_fma_f32 v233, v233, v48, -v225
	v_fma_f32 v234, v234, v48, -v226
	v_fma_f32 v235, v235, v48, -v227
	v_cvt_pk_bf16_f32 v244, v228, v229
	v_cvt_pk_bf16_f32 v245, v230, v231
	v_cvt_pk_bf16_f32 v246, v232, v233
	v_cvt_pk_bf16_f32 v247, v234, v235
	global_store_dwordx4 v7, v[244:247], s[84:85]
	s_nop 1
	s_waitcnt vmcnt(25)
	v_lshlrev_b32_e32 v220, 16, v72
	v_and_b32_e32 v221, 0xffff0000, v72
	v_lshlrev_b32_e32 v222, 16, v73
	v_and_b32_e32 v223, 0xffff0000, v73
	v_lshlrev_b32_e32 v224, 16, v74
	v_and_b32_e32 v225, 0xffff0000, v74
	v_lshlrev_b32_e32 v226, 16, v75
	v_and_b32_e32 v227, 0xffff0000, v75
	v_mov_b32_e32 v228, v220
	v_mov_b32_e32 v229, v221
	v_mov_b32_e32 v230, v222
	v_mov_b32_e32 v231, v223
	v_mov_b32_e32 v232, v224
	v_mov_b32_e32 v233, v225
	v_mov_b32_e32 v234, v226
	v_mov_b32_e32 v235, v227
	v_lshlrev_b32_e32 v236, 16, v76
	v_and_b32_e32 v237, 0xffff0000, v76
	v_lshlrev_b32_e32 v238, 16, v77
	v_and_b32_e32 v239, 0xffff0000, v77
	v_lshlrev_b32_e32 v240, 16, v78
	v_and_b32_e32 v241, 0xffff0000, v78
	v_lshlrev_b32_e32 v242, 16, v79
	v_and_b32_e32 v243, 0xffff0000, v79
	v_fmac_f32_e32 v228, v236, v33
	v_fmac_f32_e32 v229, v237, v33
	v_fmac_f32_e32 v230, v238, v33
	v_fmac_f32_e32 v231, v239, v33
	v_fmac_f32_e32 v232, v240, v33
	v_fmac_f32_e32 v233, v241, v33
	v_fmac_f32_e32 v234, v242, v33
	v_fmac_f32_e32 v235, v243, v33
	v_lshlrev_b32_e32 v236, 16, v80
	v_and_b32_e32 v237, 0xffff0000, v80
	v_lshlrev_b32_e32 v238, 16, v81
	v_and_b32_e32 v239, 0xffff0000, v81
	v_lshlrev_b32_e32 v240, 16, v82
	v_and_b32_e32 v241, 0xffff0000, v82
	v_lshlrev_b32_e32 v242, 16, v83
	v_and_b32_e32 v243, 0xffff0000, v83
	v_fmac_f32_e32 v228, v236, v34
	v_fmac_f32_e32 v229, v237, v34
	v_fmac_f32_e32 v230, v238, v34
	v_fmac_f32_e32 v231, v239, v34
	v_fmac_f32_e32 v232, v240, v34
	v_fmac_f32_e32 v233, v241, v34
	v_fmac_f32_e32 v234, v242, v34
	v_fmac_f32_e32 v235, v243, v34
	v_lshlrev_b32_e32 v236, 16, v84
	v_and_b32_e32 v237, 0xffff0000, v84
	v_lshlrev_b32_e32 v238, 16, v85
	v_and_b32_e32 v239, 0xffff0000, v85
	v_lshlrev_b32_e32 v240, 16, v86
	v_and_b32_e32 v241, 0xffff0000, v86
	v_lshlrev_b32_e32 v242, 16, v87
	v_and_b32_e32 v243, 0xffff0000, v87
	v_fmac_f32_e32 v228, v236, v35
	v_fmac_f32_e32 v229, v237, v35
	v_fmac_f32_e32 v230, v238, v35
	v_fmac_f32_e32 v231, v239, v35
	v_fmac_f32_e32 v232, v240, v35
	v_fmac_f32_e32 v233, v241, v35
	v_fmac_f32_e32 v234, v242, v35
	v_fmac_f32_e32 v235, v243, v35
	v_fma_f32 v228, v228, v49, -v220
	v_fma_f32 v229, v229, v49, -v221
	v_fma_f32 v230, v230, v49, -v222
	v_fma_f32 v231, v231, v49, -v223
	v_fma_f32 v232, v232, v49, -v224
	v_fma_f32 v233, v233, v49, -v225
	v_fma_f32 v234, v234, v49, -v226
	v_fma_f32 v235, v235, v49, -v227
	v_cvt_pk_bf16_f32 v244, v228, v229
	v_cvt_pk_bf16_f32 v245, v230, v231
	v_cvt_pk_bf16_f32 v246, v232, v233
	v_cvt_pk_bf16_f32 v247, v234, v235
	global_store_dwordx4 v7, v[244:247], s[84:85] offset:512
	s_nop 1
	s_waitcnt vmcnt(18)
	v_lshlrev_b32_e32 v220, 16, v88
	v_and_b32_e32 v221, 0xffff0000, v88
	v_lshlrev_b32_e32 v222, 16, v89
	v_and_b32_e32 v223, 0xffff0000, v89
	v_lshlrev_b32_e32 v224, 16, v90
	v_and_b32_e32 v225, 0xffff0000, v90
	v_lshlrev_b32_e32 v226, 16, v91
	v_and_b32_e32 v227, 0xffff0000, v91
	v_mov_b32_e32 v228, v220
	v_mov_b32_e32 v229, v221
	v_mov_b32_e32 v230, v222
	v_mov_b32_e32 v231, v223
	v_mov_b32_e32 v232, v224
	v_mov_b32_e32 v233, v225
	v_mov_b32_e32 v234, v226
	v_mov_b32_e32 v235, v227
	v_lshlrev_b32_e32 v236, 16, v92
	v_and_b32_e32 v237, 0xffff0000, v92
	v_lshlrev_b32_e32 v238, 16, v93
	v_and_b32_e32 v239, 0xffff0000, v93
	v_lshlrev_b32_e32 v240, 16, v94
	v_and_b32_e32 v241, 0xffff0000, v94
	v_lshlrev_b32_e32 v242, 16, v95
	v_and_b32_e32 v243, 0xffff0000, v95
	v_fmac_f32_e32 v228, v236, v33
	v_fmac_f32_e32 v229, v237, v33
	v_fmac_f32_e32 v230, v238, v33
	v_fmac_f32_e32 v231, v239, v33
	v_fmac_f32_e32 v232, v240, v33
	v_fmac_f32_e32 v233, v241, v33
	v_fmac_f32_e32 v234, v242, v33
	v_fmac_f32_e32 v235, v243, v33
	v_lshlrev_b32_e32 v236, 16, v96
	v_and_b32_e32 v237, 0xffff0000, v96
	v_lshlrev_b32_e32 v238, 16, v97
	v_and_b32_e32 v239, 0xffff0000, v97
	v_lshlrev_b32_e32 v240, 16, v98
	v_and_b32_e32 v241, 0xffff0000, v98
	v_lshlrev_b32_e32 v242, 16, v99
	v_and_b32_e32 v243, 0xffff0000, v99
	v_fmac_f32_e32 v228, v236, v34
	v_fmac_f32_e32 v229, v237, v34
	v_fmac_f32_e32 v230, v238, v34
	v_fmac_f32_e32 v231, v239, v34
	v_fmac_f32_e32 v232, v240, v34
	v_fmac_f32_e32 v233, v241, v34
	v_fmac_f32_e32 v234, v242, v34
; __device__ __forceinline__ unsigned pk2(float lo, float hi) { const f32x2_t v = {lo, hi}; const bf16x2_t b = __builtin_convertvector(v, bf16x2_t); return __builtin_bit_cast(unsigned, b); }
; template <int W>
; __device__ __forceinline__ void pool_item(const Params& p, const bf16_t* PROJ, bf16_t* D, int r, int c0) {
;     ...
;         u32x4 v[W - 1];
; #pragma unroll
;         for (int i = 1; i < W; ++i) v[i - 1] = *(const u32x4*)(PROJ + (size_t)(r - (i <= t ? i : 0)) * NQ + c0);
; #pragma unroll
;         for (int i = 1; i < W; ++i) acc8(sum, v[i - 1], (i <= t) ? 1.f : 0.f);
;     } else {
;         const int s = r - MP; cnt = (float)W; const float* sp = p.in[4] + (size_t)s * 15 * 1024 + c0;
;         f32x4 a[W - 1], b[W - 1];
; #pragma unroll
;         for (int i = 0; i < W - 1; ++i) { a[i] = *(const f32x4*)(sp + (size_t)(14 - i) * 1024); b[i] = *(const f32x4*)(sp + (size_t)(14 - i) * 1024 + 4); }
; #pragma unroll
;         for (int i = 0; i < W - 1; ++i) { sum[0] += a[i].x; sum[1] += a[i].y; sum[2] += a[i].z; sum[3] += a[i].w; sum[4] += b[i].x; sum[5] += b[i].y; sum[6] += b[i].z; sum[7] += b[i].w; }
;     }
;     const float inv = 1.0f / cnt; u32x4 o;
;     o.x = pk2(sum[0] * inv - uu[0], sum[1] * inv - uu[1]); o.y = pk2(sum[2] * inv - uu[2], sum[3] * inv - uu[3]);
;     o.z = pk2(sum[4] * inv - uu[4], sum[5] * inv - uu[5]); o.w = pk2(sum[6] * inv - uu[6], sum[7] * inv - uu[7]);
;     *(u32x4*)(D + (size_t)r * 1024 + c0) = o;
	v_fmac_f32_e32 v235, v243, v34
	v_lshlrev_b32_e32 v236, 16, v100
	v_and_b32_e32 v237, 0xffff0000, v100
	v_lshlrev_b32_e32 v238, 16, v101
	v_and_b32_e32 v239, 0xffff0000, v101
	v_lshlrev_b32_e32 v240, 16, v102
	v_and_b32_e32 v241, 0xffff0000, v102
	v_lshlrev_b32_e32 v242, 16, v103
	v_and_b32_e32 v243, 0xffff0000, v103
	v_fmac_f32_e32 v228, v236, v35
	v_fmac_f32_e32 v229, v237, v35
	v_fmac_f32_e32 v230, v238, v35
	v_fmac_f32_e32 v231, v239, v35
	v_fmac_f32_e32 v232, v240, v35
	v_fmac_f32_e32 v233, v241, v35
	v_fmac_f32_e32 v234, v242, v35
	v_fmac_f32_e32 v235, v243, v35
	v_lshlrev_b32_e32 v236, 16, v104
	v_and_b32_e32 v237, 0xffff0000, v104
	v_lshlrev_b32_e32 v238, 16, v105
	v_and_b32_e32 v239, 0xffff0000, v105
	v_lshlrev_b32_e32 v240, 16, v106
	v_and_b32_e32 v241, 0xffff0000, v106
	v_lshlrev_b32_e32 v242, 16, v107
	v_and_b32_e32 v243, 0xffff0000, v107
	v_fmac_f32_e32 v228, v236, v36
	v_fmac_f32_e32 v229, v237, v36
	v_fmac_f32_e32 v230, v238, v36
	v_fmac_f32_e32 v231, v239, v36
	v_fmac_f32_e32 v232, v240, v36
	v_fmac_f32_e32 v233, v241, v36
	v_fmac_f32_e32 v234, v242, v36
	v_fmac_f32_e32 v235, v243, v36
	v_lshlrev_b32_e32 v236, 16, v108
	v_and_b32_e32 v237, 0xffff0000, v108
	v_lshlrev_b32_e32 v238, 16, v109
	v_and_b32_e32 v239, 0xffff0000, v109
	v_lshlrev_b32_e32 v240, 16, v110
	v_and_b32_e32 v241, 0xffff0000, v110
	v_lshlrev_b32_e32 v242, 16, v111
	v_and_b32_e32 v243, 0xffff0000, v111
	v_fmac_f32_e32 v228, v236, v37
	v_fmac_f32_e32 v229, v237, v37
	v_fmac_f32_e32 v230, v238, v37
	v_fmac_f32_e32 v231, v239, v37
	v_fmac_f32_e32 v232, v240, v37
	v_fmac_f32_e32 v233, v241, v37
	v_fmac_f32_e32 v234, v242, v37
	v_fmac_f32_e32 v235, v243, v37
	v_lshlrev_b32_e32 v236, 16, v112
	v_and_b32_e32 v237, 0xffff0000, v112
	v_lshlrev_b32_e32 v238, 16, v113
	v_and_b32_e32 v239, 0xffff0000, v113
	v_lshlrev_b32_e32 v240, 16, v114
	v_and_b32_e32 v241, 0xffff0000, v114
	v_lshlrev_b32_e32 v242, 16, v115
	v_and_b32_e32 v243, 0xffff0000, v115
	v_fmac_f32_e32 v228, v236, v38
	v_fmac_f32_e32 v229, v237, v38
	v_fmac_f32_e32 v230, v238, v38
	v_fmac_f32_e32 v231, v239, v38
	v_fmac_f32_e32 v232, v240, v38
	v_fmac_f32_e32 v233, v241, v38
	v_fmac_f32_e32 v234, v242, v38
	v_fmac_f32_e32 v235, v243, v38
	v_lshlrev_b32_e32 v236, 16, v116
	v_and_b32_e32 v237, 0xffff0000, v116
	v_lshlrev_b32_e32 v238, 16, v117
	v_and_b32_e32 v239, 0xffff0000, v117
	v_lshlrev_b32_e32 v240, 16, v118
	v_and_b32_e32 v241, 0xffff0000, v118
	v_lshlrev_b32_e32 v242, 16, v119
	v_and_b32_e32 v243, 0xffff0000, v119
	v_fmac_f32_e32 v228, v236, v39
	v_fmac_f32_e32 v229, v237, v39
	v_fmac_f32_e32 v230, v238, v39
	v_fmac_f32_e32 v231, v239, v39
	v_fmac_f32_e32 v232, v240, v39
	v_fmac_f32_e32 v233, v241, v39
	v_fmac_f32_e32 v234, v242, v39
	v_fmac_f32_e32 v235, v243, v39
	v_fma_f32 v228, v228, v50, -v220
	v_fma_f32 v229, v229, v50, -v221
	v_fma_f32 v230, v230, v50, -v222
	v_fma_f32 v231, v231, v50, -v223
	v_fma_f32 v232, v232, v50, -v224
	v_fma_f32 v233, v233, v50, -v225
	v_fma_f32 v234, v234, v50, -v226
	v_fma_f32 v235, v235, v50, -v227
	v_cvt_pk_bf16_f32 v244, v228, v229
	v_cvt_pk_bf16_f32 v245, v230, v231
	v_cvt_pk_bf16_f32 v246, v232, v233
	v_cvt_pk_bf16_f32 v247, v234, v235
	global_store_dwordx4 v7, v[244:247], s[84:85] offset:1024
	s_nop 1
	s_waitcnt vmcnt(3)
	v_lshlrev_b32_e32 v220, 16, v120
	v_and_b32_e32 v221, 0xffff0000, v120
	v_lshlrev_b32_e32 v222, 16, v121
	v_and_b32_e32 v223, 0xffff0000, v121
	v_lshlrev_b32_e32 v224, 16, v122
	v_and_b32_e32 v225, 0xffff0000, v122
	v_lshlrev_b32_e32 v226, 16, v123
	v_and_b32_e32 v227, 0xffff0000, v123
	v_mov_b32_e32 v228, v220
	v_mov_b32_e32 v229, v221
	v_mov_b32_e32 v230, v222
	v_mov_b32_e32 v231, v223
	v_mov_b32_e32 v232, v224
	v_mov_b32_e32 v233, v225
	v_mov_b32_e32 v234, v226
	v_mov_b32_e32 v235, v227
	v_lshlrev_b32_e32 v236, 16, v124
	v_and_b32_e32 v237, 0xffff0000, v124
	v_lshlrev_b32_e32 v238, 16, v125
	v_and_b32_e32 v239, 0xffff0000, v125
	v_lshlrev_b32_e32 v240, 16, v126
	v_and_b32_e32 v241, 0xffff0000, v126
	v_lshlrev_b32_e32 v242, 16, v127
	v_and_b32_e32 v243, 0xffff0000, v127
	v_fmac_f32_e32 v228, v236, v33
	v_fmac_f32_e32 v229, v237, v33
	v_fmac_f32_e32 v230, v238, v33
	v_fmac_f32_e32 v231, v239, v33
	v_fmac_f32_e32 v232, v240, v33
	v_fmac_f32_e32 v233, v241, v33
	v_fmac_f32_e32 v234, v242, v33
	v_fmac_f32_e32 v235, v243, v33
	v_lshlrev_b32_e32 v236, 16, v128
	v_and_b32_e32 v237, 0xffff0000, v128
	v_lshlrev_b32_e32 v238, 16, v129
	v_and_b32_e32 v239, 0xffff0000, v129
	v_lshlrev_b32_e32 v240, 16, v130
	v_and_b32_e32 v241, 0xffff0000, v130
	v_lshlrev_b32_e32 v242, 16, v131
	v_and_b32_e32 v243, 0xffff0000, v131
	v_fmac_f32_e32 v228, v236, v34
	v_fmac_f32_e32 v229, v237, v34
	v_fmac_f32_e32 v230, v238, v34
	v_fmac_f32_e32 v231, v239, v34
	v_fmac_f32_e32 v232, v240, v34
	v_fmac_f32_e32 v233, v241, v34
	v_fmac_f32_e32 v234, v242, v34
	v_fmac_f32_e32 v235, v243, v34
	v_lshlrev_b32_e32 v236, 16, v132
	v_and_b32_e32 v237, 0xffff0000, v132
	v_lshlrev_b32_e32 v238, 16, v133
	v_and_b32_e32 v239, 0xffff0000, v133
	v_lshlrev_b32_e32 v240, 16, v134
	v_and_b32_e32 v241, 0xffff0000, v134
	v_lshlrev_b32_e32 v242, 16, v135
	v_and_b32_e32 v243, 0xffff0000, v135
	v_fmac_f32_e32 v228, v236, v35
	v_fmac_f32_e32 v229, v237, v35
	v_fmac_f32_e32 v230, v238, v35
	v_fmac_f32_e32 v231, v239, v35
	v_fmac_f32_e32 v232, v240, v35
	v_fmac_f32_e32 v233, v241, v35
	v_fmac_f32_e32 v234, v242, v35
	v_fmac_f32_e32 v235, v243, v35
	v_lshlrev_b32_e32 v236, 16, v136
	v_and_b32_e32 v237, 0xffff0000, v136
	v_lshlrev_b32_e32 v238, 16, v137
	v_and_b32_e32 v239, 0xffff0000, v137
	v_lshlrev_b32_e32 v240, 16, v138
	v_and_b32_e32 v241, 0xffff0000, v138
	v_lshlrev_b32_e32 v242, 16, v139
; __device__ __forceinline__ unsigned pk2(float lo, float hi) { const f32x2_t v = {lo, hi}; const bf16x2_t b = __builtin_convertvector(v, bf16x2_t); return __builtin_bit_cast(unsigned, b); }
; template <int W>
; __device__ __forceinline__ void pool_item(const Params& p, const bf16_t* PROJ, bf16_t* D, int r, int c0) {
;     ...
;         u32x4 v[W - 1];
; #pragma unroll
;         for (int i = 1; i < W; ++i) v[i - 1] = *(const u32x4*)(PROJ + (size_t)(r - (i <= t ? i : 0)) * NQ + c0);
; #pragma unroll
;         for (int i = 1; i < W; ++i) acc8(sum, v[i - 1], (i <= t) ? 1.f : 0.f);
;     } else {
;         const int s = r - MP; cnt = (float)W; const float* sp = p.in[4] + (size_t)s * 15 * 1024 + c0;
;         f32x4 a[W - 1], b[W - 1];
; #pragma unroll
;         for (int i = 0; i < W - 1; ++i) { a[i] = *(const f32x4*)(sp + (size_t)(14 - i) * 1024); b[i] = *(const f32x4*)(sp + (size_t)(14 - i) * 1024 + 4); }
; #pragma unroll
;         for (int i = 0; i < W - 1; ++i) { sum[0] += a[i].x; sum[1] += a[i].y; sum[2] += a[i].z; sum[3] += a[i].w; sum[4] += b[i].x; sum[5] += b[i].y; sum[6] += b[i].z; sum[7] += b[i].w; }
;     }
;     const float inv = 1.0f / cnt; u32x4 o;
;     o.x = pk2(sum[0] * inv - uu[0], sum[1] * inv - uu[1]); o.y = pk2(sum[2] * inv - uu[2], sum[3] * inv - uu[3]);
;     o.z = pk2(sum[4] * inv - uu[4], sum[5] * inv - uu[5]); o.w = pk2(sum[6] * inv - uu[6], sum[7] * inv - uu[7]);
;     *(u32x4*)(D + (size_t)r * 1024 + c0) = o;
; __device__ __forceinline__ void phase_pool_d(const Params& p, int wave_s) {
;     ...
;     for (int idx = blockIdx.x * 512 + tid; idx < total; idx += gridDim.x * 512) {
;         const int r = idx >> 5, ch = idx & 31;
;         pool_item<2>(p, PROJ, D, r, ch * 8);
;         pool_item<4>(p, PROJ, D, r, 256 + ch * 8);
;         pool_item<8>(p, PROJ, D, r, 512 + ch * 8);
;         pool_item<16>(p, PROJ, D, r, 768 + ch * 8);
;     }
	v_and_b32_e32 v243, 0xffff0000, v139
	v_fmac_f32_e32 v228, v236, v36
	v_fmac_f32_e32 v229, v237, v36
	v_fmac_f32_e32 v230, v238, v36
	v_fmac_f32_e32 v231, v239, v36
	v_fmac_f32_e32 v232, v240, v36
	v_fmac_f32_e32 v233, v241, v36
	v_fmac_f32_e32 v234, v242, v36
	v_fmac_f32_e32 v235, v243, v36
	v_lshlrev_b32_e32 v236, 16, v140
	v_and_b32_e32 v237, 0xffff0000, v140
	v_lshlrev_b32_e32 v238, 16, v141
	v_and_b32_e32 v239, 0xffff0000, v141
	v_lshlrev_b32_e32 v240, 16, v142
	v_and_b32_e32 v241, 0xffff0000, v142
	v_lshlrev_b32_e32 v242, 16, v143
	v_and_b32_e32 v243, 0xffff0000, v143
	v_fmac_f32_e32 v228, v236, v37
	v_fmac_f32_e32 v229, v237, v37
	v_fmac_f32_e32 v230, v238, v37
	v_fmac_f32_e32 v231, v239, v37
	v_fmac_f32_e32 v232, v240, v37
	v_fmac_f32_e32 v233, v241, v37
	v_fmac_f32_e32 v234, v242, v37
	v_fmac_f32_e32 v235, v243, v37
	v_lshlrev_b32_e32 v236, 16, v144
	v_and_b32_e32 v237, 0xffff0000, v144
	v_lshlrev_b32_e32 v238, 16, v145
	v_and_b32_e32 v239, 0xffff0000, v145
	v_lshlrev_b32_e32 v240, 16, v146
	v_and_b32_e32 v241, 0xffff0000, v146
	v_lshlrev_b32_e32 v242, 16, v147
	v_and_b32_e32 v243, 0xffff0000, v147
	v_fmac_f32_e32 v228, v236, v38
	v_fmac_f32_e32 v229, v237, v38
	v_fmac_f32_e32 v230, v238, v38
	v_fmac_f32_e32 v231, v239, v38
	v_fmac_f32_e32 v232, v240, v38
	v_fmac_f32_e32 v233, v241, v38
	v_fmac_f32_e32 v234, v242, v38
	v_fmac_f32_e32 v235, v243, v38
	v_lshlrev_b32_e32 v236, 16, v148
	v_and_b32_e32 v237, 0xffff0000, v148
	v_lshlrev_b32_e32 v238, 16, v149
	v_and_b32_e32 v239, 0xffff0000, v149
	v_lshlrev_b32_e32 v240, 16, v150
	v_and_b32_e32 v241, 0xffff0000, v150
	v_lshlrev_b32_e32 v242, 16, v151
	v_and_b32_e32 v243, 0xffff0000, v151
	v_fmac_f32_e32 v228, v236, v39
	v_fmac_f32_e32 v229, v237, v39
	v_fmac_f32_e32 v230, v238, v39
	v_fmac_f32_e32 v231, v239, v39
	v_fmac_f32_e32 v232, v240, v39
	v_fmac_f32_e32 v233, v241, v39
	v_fmac_f32_e32 v234, v242, v39
	v_fmac_f32_e32 v235, v243, v39
	v_lshlrev_b32_e32 v236, 16, v152
	v_and_b32_e32 v237, 0xffff0000, v152
	v_lshlrev_b32_e32 v238, 16, v153
	v_and_b32_e32 v239, 0xffff0000, v153
	v_lshlrev_b32_e32 v240, 16, v154
	v_and_b32_e32 v241, 0xffff0000, v154
	v_lshlrev_b32_e32 v242, 16, v155
	v_and_b32_e32 v243, 0xffff0000, v155
	v_fmac_f32_e32 v228, v236, v40
	v_fmac_f32_e32 v229, v237, v40
	v_fmac_f32_e32 v230, v238, v40
	v_fmac_f32_e32 v231, v239, v40
	v_fmac_f32_e32 v232, v240, v40
	v_fmac_f32_e32 v233, v241, v40
	v_fmac_f32_e32 v234, v242, v40
	v_fmac_f32_e32 v235, v243, v40
	v_lshlrev_b32_e32 v236, 16, v156
	v_and_b32_e32 v237, 0xffff0000, v156
	v_lshlrev_b32_e32 v238, 16, v157
	v_and_b32_e32 v239, 0xffff0000, v157
	v_lshlrev_b32_e32 v240, 16, v158
	v_and_b32_e32 v241, 0xffff0000, v158
	v_lshlrev_b32_e32 v242, 16, v159
	v_and_b32_e32 v243, 0xffff0000, v159
	v_fmac_f32_e32 v228, v236, v41
	v_fmac_f32_e32 v229, v237, v41
	v_fmac_f32_e32 v230, v238, v41
	v_fmac_f32_e32 v231, v239, v41
	v_fmac_f32_e32 v232, v240, v41
	v_fmac_f32_e32 v233, v241, v41
	v_fmac_f32_e32 v234, v242, v41
	v_fmac_f32_e32 v235, v243, v41
	v_lshlrev_b32_e32 v236, 16, v160
	v_and_b32_e32 v237, 0xffff0000, v160
	v_lshlrev_b32_e32 v238, 16, v161
	v_and_b32_e32 v239, 0xffff0000, v161
	v_lshlrev_b32_e32 v240, 16, v162
	v_and_b32_e32 v241, 0xffff0000, v162
	v_lshlrev_b32_e32 v242, 16, v163
	v_and_b32_e32 v243, 0xffff0000, v163
	v_fmac_f32_e32 v228, v236, v42
	v_fmac_f32_e32 v229, v237, v42
	v_fmac_f32_e32 v230, v238, v42
	v_fmac_f32_e32 v231, v239, v42
	v_fmac_f32_e32 v232, v240, v42
	v_fmac_f32_e32 v233, v241, v42
	v_fmac_f32_e32 v234, v242, v42
	v_fmac_f32_e32 v235, v243, v42
	v_lshlrev_b32_e32 v236, 16, v164
	v_and_b32_e32 v237, 0xffff0000, v164
	v_lshlrev_b32_e32 v238, 16, v165
	v_and_b32_e32 v239, 0xffff0000, v165
	v_lshlrev_b32_e32 v240, 16, v166
	v_and_b32_e32 v241, 0xffff0000, v166
	v_lshlrev_b32_e32 v242, 16, v167
	v_and_b32_e32 v243, 0xffff0000, v167
	v_fmac_f32_e32 v228, v236, v43
	v_fmac_f32_e32 v229, v237, v43
	v_fmac_f32_e32 v230, v238, v43
	v_fmac_f32_e32 v231, v239, v43
	v_fmac_f32_e32 v232, v240, v43
	v_fmac_f32_e32 v233, v241, v43
	v_fmac_f32_e32 v234, v242, v43
	v_fmac_f32_e32 v235, v243, v43
	v_lshlrev_b32_e32 v236, 16, v168
	v_and_b32_e32 v237, 0xffff0000, v168
	v_lshlrev_b32_e32 v238, 16, v169
	v_and_b32_e32 v239, 0xffff0000, v169
	v_lshlrev_b32_e32 v240, 16, v170
	v_and_b32_e32 v241, 0xffff0000, v170
	v_lshlrev_b32_e32 v242, 16, v171
	v_and_b32_e32 v243, 0xffff0000, v171
	v_fmac_f32_e32 v228, v236, v44
	v_fmac_f32_e32 v229, v237, v44
	v_fmac_f32_e32 v230, v238, v44
	v_fmac_f32_e32 v231, v239, v44
	v_fmac_f32_e32 v232, v240, v44
	v_fmac_f32_e32 v233, v241, v44
	v_fmac_f32_e32 v234, v242, v44
	v_fmac_f32_e32 v235, v243, v44
	v_lshlrev_b32_e32 v236, 16, v172
	v_and_b32_e32 v237, 0xffff0000, v172
	v_lshlrev_b32_e32 v238, 16, v173
	v_and_b32_e32 v239, 0xffff0000, v173
	v_lshlrev_b32_e32 v240, 16, v174
	v_and_b32_e32 v241, 0xffff0000, v174
	v_lshlrev_b32_e32 v242, 16, v175
	v_and_b32_e32 v243, 0xffff0000, v175
	v_fmac_f32_e32 v228, v236, v45
	v_fmac_f32_e32 v229, v237, v45
	v_fmac_f32_e32 v230, v238, v45
	v_fmac_f32_e32 v231, v239, v45
	v_fmac_f32_e32 v232, v240, v45
	v_fmac_f32_e32 v233, v241, v45
	v_fmac_f32_e32 v234, v242, v45
	v_fmac_f32_e32 v235, v243, v45
	v_lshlrev_b32_e32 v236, 16, v176
	v_and_b32_e32 v237, 0xffff0000, v176
	v_lshlrev_b32_e32 v238, 16, v177
	v_and_b32_e32 v239, 0xffff0000, v177
	v_lshlrev_b32_e32 v240, 16, v178
	v_and_b32_e32 v241, 0xffff0000, v178
	v_lshlrev_b32_e32 v242, 16, v179
	v_and_b32_e32 v243, 0xffff0000, v179
	v_fmac_f32_e32 v228, v236, v46
	v_fmac_f32_e32 v229, v237, v46
	v_fmac_f32_e32 v230, v238, v46
	v_fmac_f32_e32 v231, v239, v46
	v_fmac_f32_e32 v232, v240, v46
	v_fmac_f32_e32 v233, v241, v46
	v_fmac_f32_e32 v234, v242, v46
	v_fmac_f32_e32 v235, v243, v46
	v_lshlrev_b32_e32 v236, 16, v180
	v_and_b32_e32 v237, 0xffff0000, v180
	v_lshlrev_b32_e32 v238, 16, v181
	v_and_b32_e32 v239, 0xffff0000, v181
	v_lshlrev_b32_e32 v240, 16, v182
	v_and_b32_e32 v241, 0xffff0000, v182
	v_lshlrev_b32_e32 v242, 16, v183
	v_and_b32_e32 v243, 0xffff0000, v183
	v_fmac_f32_e32 v228, v236, v47
	v_fmac_f32_e32 v229, v237, v47
	v_fmac_f32_e32 v230, v238, v47
	v_fmac_f32_e32 v231, v239, v47
	v_fmac_f32_e32 v232, v240, v47
	v_fmac_f32_e32 v233, v241, v47
	v_fmac_f32_e32 v234, v242, v47
	v_fmac_f32_e32 v235, v243, v47
	v_fma_f32 v228, v228, v51, -v220
	v_fma_f32 v229, v229, v51, -v221
	v_fma_f32 v230, v230, v51, -v222
	v_fma_f32 v231, v231, v51, -v223
	v_fma_f32 v232, v232, v51, -v224
	v_fma_f32 v233, v233, v51, -v225
	v_fma_f32 v234, v234, v51, -v226
	v_fma_f32 v235, v235, v51, -v227
	v_cvt_pk_bf16_f32 v244, v228, v229
	v_cvt_pk_bf16_f32 v245, v230, v231
	v_cvt_pk_bf16_f32 v246, v232, v233
	v_cvt_pk_bf16_f32 v247, v234, v235
	global_store_dwordx4 v7, v[244:247], s[84:85] offset:1536
	s_nop 1
	v_add_u32_e32 v2, 0x20000, v2
	s_add_i32 s86, s86, 1
	s_cmp_lt_u32 s86, 2
	s_cbranch_scc1 .Lpoold_loop
; __device__ __forceinline__ unsigned pk2(float lo, float hi) { const f32x2_t v = {lo, hi}; const bf16x2_t b = __builtin_convertvector(v, bf16x2_t); return __builtin_bit_cast(unsigned, b); }
; template <int W>
; __device__ __forceinline__ void pool_item(const Params& p, const bf16_t* PROJ, bf16_t* D, int r, int c0) {
;     ...
;     } else {
;         const int s = r - MP; cnt = (float)W; const float* sp = p.in[4] + (size_t)s * 15 * 1024 + c0;
;         f32x4 a[W - 1], b[W - 1];
; #pragma unroll
;         for (int i = 0; i < W - 1; ++i) { a[i] = *(const f32x4*)(sp + (size_t)(14 - i) * 1024); b[i] = *(const f32x4*)(sp + (size_t)(14 - i) * 1024 + 4); }
; #pragma unroll
;         for (int i = 0; i < W - 1; ++i) { sum[0] += a[i].x; sum[1] += a[i].y; sum[2] += a[i].z; sum[3] += a[i].w; sum[4] += b[i].x; sum[5] += b[i].y; sum[6] += b[i].z; sum[7] += b[i].w; }
;     }
;     const float inv = 1.0f / cnt; u32x4 o;
;     o.x = pk2(sum[0] * inv - uu[0], sum[1] * inv - uu[1]); o.y = pk2(sum[2] * inv - uu[2], sum[3] * inv - uu[3]);
;     o.z = pk2(sum[4] * inv - uu[4], sum[5] * inv - uu[5]); o.w = pk2(sum[6] * inv - uu[6], sum[7] * inv - uu[7]);
;     *(u32x4*)(D + (size_t)r * 1024 + c0) = o;
	s_cmp_gt_u32 s2, 7
	s_cbranch_scc1 .Lpoold_done
	v_lshrrev_b32_e32 v3, 5, v2
	v_and_b32_e32 v5, 31, v2
	v_lshlrev_b32_e32 v5, 4, v5
	v_mul_u32_u24_e32 v6, 0x4800, v3
	v_add_u32_e32 v6, v6, v5
	v_lshl_add_u32 v7, v3, 11, v5
	v_add_u32_e32 v8, 0xffffe000, v3
	v_mul_u32_u24_e32 v8, 0xf000, v8
	v_lshl_add_u32 v8, v5, 1, v8
	global_load_dwordx4 v[64:67], v6, s[28:29]
	s_add_u32 s88, s60, 0xe000
	s_addc_u32 s89, s61, 0
	global_load_dwordx4 v[68:71], v8, s[88:89]
	global_load_dwordx4 v[72:75], v8, s[88:89] offset:16
	s_waitcnt vmcnt(0)
	v_lshlrev_b32_e32 v220, 16, v64
	v_and_b32_e32 v221, 0xffff0000, v64
	v_lshlrev_b32_e32 v222, 16, v65
	v_and_b32_e32 v223, 0xffff0000, v65
	v_lshlrev_b32_e32 v224, 16, v66
	v_and_b32_e32 v225, 0xffff0000, v66
	v_lshlrev_b32_e32 v226, 16, v67
	v_and_b32_e32 v227, 0xffff0000, v67
	v_mov_b32_e32 v228, v220
	v_mov_b32_e32 v229, v221
	v_mov_b32_e32 v230, v222
	v_mov_b32_e32 v231, v223
	v_mov_b32_e32 v232, v224
	v_mov_b32_e32 v233, v225
	v_mov_b32_e32 v234, v226
	v_mov_b32_e32 v235, v227
	v_add_f32_e32 v228, v228, v68
	v_add_f32_e32 v229, v229, v69
	v_add_f32_e32 v230, v230, v70
	v_add_f32_e32 v231, v231, v71
	v_add_f32_e32 v232, v232, v72
	v_add_f32_e32 v233, v233, v73
	v_add_f32_e32 v234, v234, v74
	v_add_f32_e32 v235, v235, v75
	v_mov_b32_e32 v48, 0x3f000000
	v_fma_f32 v228, v228, v48, -v220
	v_fma_f32 v229, v229, v48, -v221
	v_fma_f32 v230, v230, v48, -v222
	v_fma_f32 v231, v231, v48, -v223
	v_fma_f32 v232, v232, v48, -v224
	v_fma_f32 v233, v233, v48, -v225
	v_fma_f32 v234, v234, v48, -v226
	v_fma_f32 v235, v235, v48, -v227
	v_cvt_pk_bf16_f32 v244, v228, v229
	v_cvt_pk_bf16_f32 v245, v230, v231
	v_cvt_pk_bf16_f32 v246, v232, v233
	v_cvt_pk_bf16_f32 v247, v234, v235
	global_store_dwordx4 v7, v[244:247], s[84:85]
	s_nop 1
	global_load_dwordx4 v[64:67], v6, s[28:29] offset:512
	s_add_u32 s88, s60, 0xe400
	s_addc_u32 s89, s61, 0
	global_load_dwordx4 v[68:71], v8, s[88:89]
	global_load_dwordx4 v[72:75], v8, s[88:89] offset:16
	s_add_u32 s88, s60, 0xd400
	s_addc_u32 s89, s61, 0
	global_load_dwordx4 v[76:79], v8, s[88:89]
	global_load_dwordx4 v[80:83], v8, s[88:89] offset:16
	s_add_u32 s88, s60, 0xc400
	s_addc_u32 s89, s61, 0
	global_load_dwordx4 v[84:87], v8, s[88:89]
	global_load_dwordx4 v[88:91], v8, s[88:89] offset:16
	s_waitcnt vmcnt(0)
	v_lshlrev_b32_e32 v220, 16, v64
	v_and_b32_e32 v221, 0xffff0000, v64
	v_lshlrev_b32_e32 v222, 16, v65
	v_and_b32_e32 v223, 0xffff0000, v65
	v_lshlrev_b32_e32 v224, 16, v66
	v_and_b32_e32 v225, 0xffff0000, v66
	v_lshlrev_b32_e32 v226, 16, v67
	v_and_b32_e32 v227, 0xffff0000, v67
	v_mov_b32_e32 v228, v220
	v_mov_b32_e32 v229, v221
	v_mov_b32_e32 v230, v222
	v_mov_b32_e32 v231, v223
	v_mov_b32_e32 v232, v224
	v_mov_b32_e32 v233, v225
	v_mov_b32_e32 v234, v226
	v_mov_b32_e32 v235, v227
	v_add_f32_e32 v228, v228, v68
	v_add_f32_e32 v229, v229, v69
	v_add_f32_e32 v230, v230, v70
	v_add_f32_e32 v231, v231, v71
	v_add_f32_e32 v232, v232, v72
	v_add_f32_e32 v233, v233, v73
	v_add_f32_e32 v234, v234, v74
	v_add_f32_e32 v235, v235, v75
	v_add_f32_e32 v228, v228, v76
	v_add_f32_e32 v229, v229, v77
	v_add_f32_e32 v230, v230, v78
	v_add_f32_e32 v231, v231, v79
	v_add_f32_e32 v232, v232, v80
	v_add_f32_e32 v233, v233, v81
	v_add_f32_e32 v234, v234, v82
	v_add_f32_e32 v235, v235, v83
	v_add_f32_e32 v228, v228, v84
	v_add_f32_e32 v229, v229, v85
	v_add_f32_e32 v230, v230, v86
	v_add_f32_e32 v231, v231, v87
	v_add_f32_e32 v232, v232, v88
	v_add_f32_e32 v233, v233, v89
	v_add_f32_e32 v234, v234, v90
	v_add_f32_e32 v235, v235, v91
	v_mov_b32_e32 v48, 0x3e800000
	v_fma_f32 v228, v228, v48, -v220
	v_fma_f32 v229, v229, v48, -v221
	v_fma_f32 v230, v230, v48, -v222
	v_fma_f32 v231, v231, v48, -v223
	v_fma_f32 v232, v232, v48, -v224
	v_fma_f32 v233, v233, v48, -v225
	v_fma_f32 v234, v234, v48, -v226
	v_fma_f32 v235, v235, v48, -v227
	v_cvt_pk_bf16_f32 v244, v228, v229
	v_cvt_pk_bf16_f32 v245, v230, v231
	v_cvt_pk_bf16_f32 v246, v232, v233
	v_cvt_pk_bf16_f32 v247, v234, v235
	global_store_dwordx4 v7, v[244:247], s[84:85] offset:512
	s_nop 1
	global_load_dwordx4 v[64:67], v6, s[28:29] offset:1024
	s_add_u32 s88, s60, 0xe800
	s_addc_u32 s89, s61, 0
	global_load_dwordx4 v[68:71], v8, s[88:89]
	global_load_dwordx4 v[72:75], v8, s[88:89] offset:16
	s_add_u32 s88, s60, 0xd800
	s_addc_u32 s89, s61, 0
	global_load_dwordx4 v[76:79], v8, s[88:89]
	global_load_dwordx4 v[80:83], v8, s[88:89] offset:16
	s_add_u32 s88, s60, 0xc800
	s_addc_u32 s89, s61, 0
	global_load_dwordx4 v[84:87], v8, s[88:89]
	global_load_dwordx4 v[88:91], v8, s[88:89] offset:16
	s_add_u32 s88, s60, 0xb800
	s_addc_u32 s89, s61, 0
	global_load_dwordx4 v[92:95], v8, s[88:89]
	global_load_dwordx4 v[96:99], v8, s[88:89] offset:16
	s_add_u32 s88, s60, 0xa800
	s_addc_u32 s89, s61, 0
	global_load_dwordx4 v[100:103], v8, s[88:89]
	global_load_dwordx4 v[104:107], v8, s[88:89] offset:16
	s_add_u32 s88, s60, 0x9800
	s_addc_u32 s89, s61, 0
	global_load_dwordx4 v[108:111], v8, s[88:89]
	global_load_dwordx4 v[112:115], v8, s[88:89] offset:16
	s_add_u32 s88, s60, 0x8800
	s_addc_u32 s89, s61, 0
	global_load_dwordx4 v[116:119], v8, s[88:89]
	global_load_dwordx4 v[120:123], v8, s[88:89] offset:16
	s_waitcnt vmcnt(0)
; __device__ __forceinline__ unsigned pk2(float lo, float hi) { const f32x2_t v = {lo, hi}; const bf16x2_t b = __builtin_convertvector(v, bf16x2_t); return __builtin_bit_cast(unsigned, b); }
; template <int W>
; __device__ __forceinline__ void pool_item(const Params& p, const bf16_t* PROJ, bf16_t* D, int r, int c0) {
;     ...
;     } else {
;         const int s = r - MP; cnt = (float)W; const float* sp = p.in[4] + (size_t)s * 15 * 1024 + c0;
;         f32x4 a[W - 1], b[W - 1];
; #pragma unroll
;         for (int i = 0; i < W - 1; ++i) { a[i] = *(const f32x4*)(sp + (size_t)(14 - i) * 1024); b[i] = *(const f32x4*)(sp + (size_t)(14 - i) * 1024 + 4); }
; #pragma unroll
;         for (int i = 0; i < W - 1; ++i) { sum[0] += a[i].x; sum[1] += a[i].y; sum[2] += a[i].z; sum[3] += a[i].w; sum[4] += b[i].x; sum[5] += b[i].y; sum[6] += b[i].z; sum[7] += b[i].w; }
;     }
;     const float inv = 1.0f / cnt; u32x4 o;
;     o.x = pk2(sum[0] * inv - uu[0], sum[1] * inv - uu[1]); o.y = pk2(sum[2] * inv - uu[2], sum[3] * inv - uu[3]);
;     o.z = pk2(sum[4] * inv - uu[4], sum[5] * inv - uu[5]); o.w = pk2(sum[6] * inv - uu[6], sum[7] * inv - uu[7]);
;     *(u32x4*)(D + (size_t)r * 1024 + c0) = o;
	v_lshlrev_b32_e32 v220, 16, v64
	v_and_b32_e32 v221, 0xffff0000, v64
	v_lshlrev_b32_e32 v222, 16, v65
	v_and_b32_e32 v223, 0xffff0000, v65
	v_lshlrev_b32_e32 v224, 16, v66
	v_and_b32_e32 v225, 0xffff0000, v66
	v_lshlrev_b32_e32 v226, 16, v67
	v_and_b32_e32 v227, 0xffff0000, v67
	v_mov_b32_e32 v228, v220
	v_mov_b32_e32 v229, v221
	v_mov_b32_e32 v230, v222
	v_mov_b32_e32 v231, v223
	v_mov_b32_e32 v232, v224
	v_mov_b32_e32 v233, v225
	v_mov_b32_e32 v234, v226
	v_mov_b32_e32 v235, v227
	v_add_f32_e32 v228, v228, v68
	v_add_f32_e32 v229, v229, v69
	v_add_f32_e32 v230, v230, v70
	v_add_f32_e32 v231, v231, v71
	v_add_f32_e32 v232, v232, v72
	v_add_f32_e32 v233, v233, v73
	v_add_f32_e32 v234, v234, v74
	v_add_f32_e32 v235, v235, v75
	v_add_f32_e32 v228, v228, v76
	v_add_f32_e32 v229, v229, v77
	v_add_f32_e32 v230, v230, v78
	v_add_f32_e32 v231, v231, v79
	v_add_f32_e32 v232, v232, v80
	v_add_f32_e32 v233, v233, v81
	v_add_f32_e32 v234, v234, v82
	v_add_f32_e32 v235, v235, v83
	v_add_f32_e32 v228, v228, v84
	v_add_f32_e32 v229, v229, v85
	v_add_f32_e32 v230, v230, v86
	v_add_f32_e32 v231, v231, v87
	v_add_f32_e32 v232, v232, v88
	v_add_f32_e32 v233, v233, v89
	v_add_f32_e32 v234, v234, v90
	v_add_f32_e32 v235, v235, v91
	v_add_f32_e32 v228, v228, v92
	v_add_f32_e32 v229, v229, v93
	v_add_f32_e32 v230, v230, v94
	v_add_f32_e32 v231, v231, v95
	v_add_f32_e32 v232, v232, v96
	v_add_f32_e32 v233, v233, v97
	v_add_f32_e32 v234, v234, v98
	v_add_f32_e32 v235, v235, v99
	v_add_f32_e32 v228, v228, v100
	v_add_f32_e32 v229, v229, v101
	v_add_f32_e32 v230, v230, v102
	v_add_f32_e32 v231, v231, v103
	v_add_f32_e32 v232, v232, v104
	v_add_f32_e32 v233, v233, v105
	v_add_f32_e32 v234, v234, v106
	v_add_f32_e32 v235, v235, v107
	v_add_f32_e32 v228, v228, v108
	v_add_f32_e32 v229, v229, v109
	v_add_f32_e32 v230, v230, v110
	v_add_f32_e32 v231, v231, v111
	v_add_f32_e32 v232, v232, v112
	v_add_f32_e32 v233, v233, v113
	v_add_f32_e32 v234, v234, v114
	v_add_f32_e32 v235, v235, v115
	v_add_f32_e32 v228, v228, v116
	v_add_f32_e32 v229, v229, v117
	v_add_f32_e32 v230, v230, v118
	v_add_f32_e32 v231, v231, v119
	v_add_f32_e32 v232, v232, v120
	v_add_f32_e32 v233, v233, v121
	v_add_f32_e32 v234, v234, v122
	v_add_f32_e32 v235, v235, v123
	v_mov_b32_e32 v48, 0x3e000000
	v_fma_f32 v228, v228, v48, -v220
	v_fma_f32 v229, v229, v48, -v221
	v_fma_f32 v230, v230, v48, -v222
	v_fma_f32 v231, v231, v48, -v223
	v_fma_f32 v232, v232, v48, -v224
	v_fma_f32 v233, v233, v48, -v225
	v_fma_f32 v234, v234, v48, -v226
	v_fma_f32 v235, v235, v48, -v227
	v_cvt_pk_bf16_f32 v244, v228, v229
	v_cvt_pk_bf16_f32 v245, v230, v231
	v_cvt_pk_bf16_f32 v246, v232, v233
	v_cvt_pk_bf16_f32 v247, v234, v235
	global_store_dwordx4 v7, v[244:247], s[84:85] offset:1024
	s_nop 1
	global_load_dwordx4 v[64:67], v6, s[28:29] offset:1536
	s_add_u32 s88, s60, 0xec00
	s_addc_u32 s89, s61, 0
	global_load_dwordx4 v[68:71], v8, s[88:89]
	global_load_dwordx4 v[72:75], v8, s[88:89] offset:16
	s_add_u32 s88, s60, 0xdc00
	s_addc_u32 s89, s61, 0
	global_load_dwordx4 v[76:79], v8, s[88:89]
	global_load_dwordx4 v[80:83], v8, s[88:89] offset:16
	s_add_u32 s88, s60, 0xcc00
	s_addc_u32 s89, s61, 0
	global_load_dwordx4 v[84:87], v8, s[88:89]
	global_load_dwordx4 v[88:91], v8, s[88:89] offset:16
	s_add_u32 s88, s60, 0xbc00
	s_addc_u32 s89, s61, 0
	global_load_dwordx4 v[92:95], v8, s[88:89]
	global_load_dwordx4 v[96:99], v8, s[88:89] offset:16
	s_add_u32 s88, s60, 0xac00
	s_addc_u32 s89, s61, 0
	global_load_dwordx4 v[100:103], v8, s[88:89]
	global_load_dwordx4 v[104:107], v8, s[88:89] offset:16
	s_add_u32 s88, s60, 0x9c00
	s_addc_u32 s89, s61, 0
	global_load_dwordx4 v[108:111], v8, s[88:89]
	global_load_dwordx4 v[112:115], v8, s[88:89] offset:16
	s_add_u32 s88, s60, 0x8c00
	s_addc_u32 s89, s61, 0
	global_load_dwordx4 v[116:119], v8, s[88:89]
	global_load_dwordx4 v[120:123], v8, s[88:89] offset:16
	s_add_u32 s88, s60, 0x7c00
	s_addc_u32 s89, s61, 0
	global_load_dwordx4 v[124:127], v8, s[88:89]
	global_load_dwordx4 v[128:131], v8, s[88:89] offset:16
	s_add_u32 s88, s60, 0x6c00
	s_addc_u32 s89, s61, 0
	global_load_dwordx4 v[132:135], v8, s[88:89]
	global_load_dwordx4 v[136:139], v8, s[88:89] offset:16
	s_add_u32 s88, s60, 0x5c00
	s_addc_u32 s89, s61, 0
	global_load_dwordx4 v[140:143], v8, s[88:89]
	global_load_dwordx4 v[144:147], v8, s[88:89] offset:16
	s_add_u32 s88, s60, 0x4c00
	s_addc_u32 s89, s61, 0
	global_load_dwordx4 v[148:151], v8, s[88:89]
	global_load_dwordx4 v[152:155], v8, s[88:89] offset:16
	s_add_u32 s88, s60, 0x3c00
	s_addc_u32 s89, s61, 0
	global_load_dwordx4 v[156:159], v8, s[88:89]
	global_load_dwordx4 v[160:163], v8, s[88:89] offset:16
	s_add_u32 s88, s60, 0x2c00
	s_addc_u32 s89, s61, 0
	global_load_dwordx4 v[164:167], v8, s[88:89]
	global_load_dwordx4 v[168:171], v8, s[88:89] offset:16
	s_add_u32 s88, s60, 0x1c00
	s_addc_u32 s89, s61, 0
	global_load_dwordx4 v[172:175], v8, s[88:89]
	global_load_dwordx4 v[176:179], v8, s[88:89] offset:16
	s_add_u32 s88, s60, 0xc00
	s_addc_u32 s89, s61, 0
	global_load_dwordx4 v[180:183], v8, s[88:89]
	global_load_dwordx4 v[184:187], v8, s[88:89] offset:16
	s_waitcnt vmcnt(0)
; __device__ __forceinline__ unsigned pk2(float lo, float hi) { const f32x2_t v = {lo, hi}; const bf16x2_t b = __builtin_convertvector(v, bf16x2_t); return __builtin_bit_cast(unsigned, b); }
; template <int W>
; __device__ __forceinline__ void pool_item(const Params& p, const bf16_t* PROJ, bf16_t* D, int r, int c0) {
;     ...
;         const int s = r - MP; cnt = (float)W; const float* sp = p.in[4] + (size_t)s * 15 * 1024 + c0;
;         f32x4 a[W - 1], b[W - 1];
; #pragma unroll
;         for (int i = 0; i < W - 1; ++i) { a[i] = *(const f32x4*)(sp + (size_t)(14 - i) * 1024); b[i] = *(const f32x4*)(sp + (size_t)(14 - i) * 1024 + 4); }
; #pragma unroll
;         for (int i = 0; i < W - 1; ++i) { sum[0] += a[i].x; sum[1] += a[i].y; sum[2] += a[i].z; sum[3] += a[i].w; sum[4] += b[i].x; sum[5] += b[i].y; sum[6] += b[i].z; sum[7] += b[i].w; }
;     }
;     const float inv = 1.0f / cnt; u32x4 o;
;     o.x = pk2(sum[0] * inv - uu[0], sum[1] * inv - uu[1]); o.y = pk2(sum[2] * inv - uu[2], sum[3] * inv - uu[3]);
;     o.z = pk2(sum[4] * inv - uu[4], sum[5] * inv - uu[5]); o.w = pk2(sum[6] * inv - uu[6], sum[7] * inv - uu[7]);
;     *(u32x4*)(D + (size_t)r * 1024 + c0) = o;
	v_lshlrev_b32_e32 v220, 16, v64
	v_and_b32_e32 v221, 0xffff0000, v64
	v_lshlrev_b32_e32 v222, 16, v65
	v_and_b32_e32 v223, 0xffff0000, v65
	v_lshlrev_b32_e32 v224, 16, v66
	v_and_b32_e32 v225, 0xffff0000, v66
	v_lshlrev_b32_e32 v226, 16, v67
	v_and_b32_e32 v227, 0xffff0000, v67
	v_mov_b32_e32 v228, v220
	v_mov_b32_e32 v229, v221
	v_mov_b32_e32 v230, v222
	v_mov_b32_e32 v231, v223
	v_mov_b32_e32 v232, v224
	v_mov_b32_e32 v233, v225
	v_mov_b32_e32 v234, v226
	v_mov_b32_e32 v235, v227
	v_add_f32_e32 v228, v228, v68
	v_add_f32_e32 v229, v229, v69
	v_add_f32_e32 v230, v230, v70
	v_add_f32_e32 v231, v231, v71
	v_add_f32_e32 v232, v232, v72
	v_add_f32_e32 v233, v233, v73
	v_add_f32_e32 v234, v234, v74
	v_add_f32_e32 v235, v235, v75
	v_add_f32_e32 v228, v228, v76
	v_add_f32_e32 v229, v229, v77
	v_add_f32_e32 v230, v230, v78
	v_add_f32_e32 v231, v231, v79
	v_add_f32_e32 v232, v232, v80
	v_add_f32_e32 v233, v233, v81
	v_add_f32_e32 v234, v234, v82
	v_add_f32_e32 v235, v235, v83
	v_add_f32_e32 v228, v228, v84
	v_add_f32_e32 v229, v229, v85
	v_add_f32_e32 v230, v230, v86
	v_add_f32_e32 v231, v231, v87
	v_add_f32_e32 v232, v232, v88
	v_add_f32_e32 v233, v233, v89
	v_add_f32_e32 v234, v234, v90
	v_add_f32_e32 v235, v235, v91
	v_add_f32_e32 v228, v228, v92
	v_add_f32_e32 v229, v229, v93
	v_add_f32_e32 v230, v230, v94
	v_add_f32_e32 v231, v231, v95
	v_add_f32_e32 v232, v232, v96
	v_add_f32_e32 v233, v233, v97
	v_add_f32_e32 v234, v234, v98
	v_add_f32_e32 v235, v235, v99
	v_add_f32_e32 v228, v228, v100
	v_add_f32_e32 v229, v229, v101
	v_add_f32_e32 v230, v230, v102
	v_add_f32_e32 v231, v231, v103
	v_add_f32_e32 v232, v232, v104
	v_add_f32_e32 v233, v233, v105
	v_add_f32_e32 v234, v234, v106
	v_add_f32_e32 v235, v235, v107
	v_add_f32_e32 v228, v228, v108
	v_add_f32_e32 v229, v229, v109
	v_add_f32_e32 v230, v230, v110
	v_add_f32_e32 v231, v231, v111
	v_add_f32_e32 v232, v232, v112
	v_add_f32_e32 v233, v233, v113
	v_add_f32_e32 v234, v234, v114
	v_add_f32_e32 v235, v235, v115
	v_add_f32_e32 v228, v228, v116
	v_add_f32_e32 v229, v229, v117
	v_add_f32_e32 v230, v230, v118
	v_add_f32_e32 v231, v231, v119
	v_add_f32_e32 v232, v232, v120
	v_add_f32_e32 v233, v233, v121
	v_add_f32_e32 v234, v234, v122
	v_add_f32_e32 v235, v235, v123
	v_add_f32_e32 v228, v228, v124
	v_add_f32_e32 v229, v229, v125
	v_add_f32_e32 v230, v230, v126
	v_add_f32_e32 v231, v231, v127
	v_add_f32_e32 v232, v232, v128
	v_add_f32_e32 v233, v233, v129
	v_add_f32_e32 v234, v234, v130
	v_add_f32_e32 v235, v235, v131
	v_add_f32_e32 v228, v228, v132
	v_add_f32_e32 v229, v229, v133
	v_add_f32_e32 v230, v230, v134
	v_add_f32_e32 v231, v231, v135
	v_add_f32_e32 v232, v232, v136
	v_add_f32_e32 v233, v233, v137
	v_add_f32_e32 v234, v234, v138
	v_add_f32_e32 v235, v235, v139
	v_add_f32_e32 v228, v228, v140
	v_add_f32_e32 v229, v229, v141
	v_add_f32_e32 v230, v230, v142
	v_add_f32_e32 v231, v231, v143
	v_add_f32_e32 v232, v232, v144
	v_add_f32_e32 v233, v233, v145
	v_add_f32_e32 v234, v234, v146
	v_add_f32_e32 v235, v235, v147
	v_add_f32_e32 v228, v228, v148
	v_add_f32_e32 v229, v229, v149
	v_add_f32_e32 v230, v230, v150
	v_add_f32_e32 v231, v231, v151
	v_add_f32_e32 v232, v232, v152
	v_add_f32_e32 v233, v233, v153
	v_add_f32_e32 v234, v234, v154
	v_add_f32_e32 v235, v235, v155
	v_add_f32_e32 v228, v228, v156
	v_add_f32_e32 v229, v229, v157
	v_add_f32_e32 v230, v230, v158
	v_add_f32_e32 v231, v231, v159
	v_add_f32_e32 v232, v232, v160
	v_add_f32_e32 v233, v233, v161
	v_add_f32_e32 v234, v234, v162
	v_add_f32_e32 v235, v235, v163
	v_add_f32_e32 v228, v228, v164
	v_add_f32_e32 v229, v229, v165
	v_add_f32_e32 v230, v230, v166
	v_add_f32_e32 v231, v231, v167
	v_add_f32_e32 v232, v232, v168
	v_add_f32_e32 v233, v233, v169
	v_add_f32_e32 v234, v234, v170
	v_add_f32_e32 v235, v235, v171
	v_add_f32_e32 v228, v228, v172
	v_add_f32_e32 v229, v229, v173
	v_add_f32_e32 v230, v230, v174
	v_add_f32_e32 v231, v231, v175
	v_add_f32_e32 v232, v232, v176
	v_add_f32_e32 v233, v233, v177
	v_add_f32_e32 v234, v234, v178
	v_add_f32_e32 v235, v235, v179
	v_add_f32_e32 v228, v228, v180
	v_add_f32_e32 v229, v229, v181
	v_add_f32_e32 v230, v230, v182
	v_add_f32_e32 v231, v231, v183
	v_add_f32_e32 v232, v232, v184
	v_add_f32_e32 v233, v233, v185
	v_add_f32_e32 v234, v234, v186
	v_add_f32_e32 v235, v235, v187
	v_mov_b32_e32 v48, 0x3d800000
	v_fma_f32 v228, v228, v48, -v220
	v_fma_f32 v229, v229, v48, -v221
	v_fma_f32 v230, v230, v48, -v222
	v_fma_f32 v231, v231, v48, -v223
	v_fma_f32 v232, v232, v48, -v224
	v_fma_f32 v233, v233, v48, -v225
	v_fma_f32 v234, v234, v48, -v226
	v_fma_f32 v235, v235, v48, -v227
	v_cvt_pk_bf16_f32 v244, v228, v229
	v_cvt_pk_bf16_f32 v245, v230, v231
	v_cvt_pk_bf16_f32 v246, v232, v233
	v_cvt_pk_bf16_f32 v247, v234, v235
	global_store_dwordx4 v7, v[244:247], s[84:85] offset:1536
	s_nop 1
.Lpoold_done:
.LBB0_661:
	s_or_b64 exec, exec, s[30:31]
	s_abs_i32 s3, s33
	v_cvt_f32_u32_e32 v0, s3
	s_mov_b32 s0, 0
	s_mov_b32 s77, -1
	v_mbcnt_lo_u32_b32 v1, -1, s0
	v_rcp_iflag_f32_e32 v0, v0
	v_mbcnt_hi_u32_b32 v1, -1, v1
	v_or_b32_e32 v208, s24, v1
	s_cmpk_gt_i32 s2, 0x7ff
	v_mul_f32_e32 v0, 0x4f7ffffe, v0
	v_cvt_u32_f32_e32 v0, v0
	s_nop 0
	v_readfirstlane_b32 s0, v0
	s_cbranch_scc1 .LBB0_786
	s_sub_i32 s1, 0, s3
	s_mul_i32 s1, s1, s0
	s_mov_b32 s7, 0
	s_mul_hi_u32 s1, s0, s1
	s_add_i32 s8, s0, s1
	s_mov_b32 s9, s7
	s_ashr_i32 s15, s33, 31
	s_lshl_b64 s[0:1], s[8:9], 11
	s_add_u32 s10, s22, 0x63a0000
	s_mul_i32 s0, s1, s3
	s_addc_u32 s11, s23, 0
	s_sub_i32 s0, 0x800, s0
	s_add_i32 s4, s1, 1
	s_sub_i32 s5, s0, s3
	s_cmp_ge_u32 s0, s3
	s_cselect_b32 s1, s4, s1
	s_cselect_b32 s0, s5, s0
	s_add_i32 s4, s1, 1
	s_cmp_ge_u32 s0, s3
	s_cselect_b32 s0, s4, s1
	s_xor_b32 s0, s0, s15
	s_sub_i32 s9, s0, s15
	s_mul_i32 s0, s9, s33
	s_cmpk_eq_i32 s0, 0x800
	s_cselect_b64 s[0:1], -1, 0
	s_add_u32 s25, s22, 0x17d2a000
	s_addc_u32 s38, s23, 0
	s_add_u32 s39, s22, 0x64a8000
	v_cndmask_b32_e64 v0, 0, 1, s[0:1]
	s_mul_i32 s9, s9, s2
	s_addc_u32 s40, s23, 0
	v_cmp_ne_u32_e64 s[0:1], 1, v0
	s_movk_i32 s41, 0x7f
	v_mov_b32_e32 v65, 0
	s_movk_i32 s42, 0x1ff
	s_add_i32 s43, 0, 0x1ca00
	s_movk_i32 s44, 0x1000
	s_movk_i32 s45, 0x2000
	s_movk_i32 s46, 0x3000
	s_movk_i32 s47, 0x4000
	s_add_i32 s48, 0, 0x1d200
	s_movk_i32 s49, 0x3ff
	s_movk_i32 s50, 0x4800
	s_add_i32 s51, 0, 0x1c8fc
	s_movk_i32 s56, 0x110
	s_movk_i32 s57, 0x84
	s_mov_b64 s[12:13], 0x4200
	s_mov_b32 s14, 0x358637bd
	s_mov_b32 s58, 0x800000
	s_movk_i32 s59, 0x4200
	s_add_i32 s60, 0, 0x4400
	s_movk_i32 s61, 0x100
	s_brev_b32 s66, 1
	s_movk_i32 s67, 0xfc00
	s_mov_b32 s76, s2
	s_branch .LBB0_664
